# everything stacked: v90 add-ons + leading-half static priority + aligned loop headers + no-sleep flag polls
# speedup vs baseline: 1.0072x; 1.0000x over previous
.LBB0_225:
	s_ashr_i32 s17, s16, 31
	s_lshl_b64 s[18:19], s[16:17], 20
	s_add_u32 s18, s30, s18
	s_addc_u32 s19, s31, s19
	s_and_b64 s[20:21], s[4:5], exec
	s_cselect_b32 s17, s19, s25
	s_cselect_b32 s54, s18, s24
	s_ashr_i32 s15, s14, 31
	s_lshl_b64 s[20:21], s[14:15], 20
	s_add_u32 s20, s34, s20
	s_addc_u32 s21, s35, s21
	s_and_b64 s[28:29], s[4:5], exec
	s_cselect_b32 s15, s21, s27
	s_cselect_b32 s55, s20, s26
	s_add_u32 s24, s24, 0x80080
	s_addc_u32 s25, s25, 0
	s_add_u32 s58, s26, 0x100
	v_mov_b32_e32 v0, 0
	v_mov_b64_e32 v[0:1], 0
	v_mov_b64_e32 v[2:3], 0
	v_mov_b64_e32 v[4:5], 0
	v_mov_b64_e32 v[6:7], 0
	v_mov_b64_e32 v[8:9], 0
	v_mov_b64_e32 v[10:11], 0
	v_mov_b64_e32 v[12:13], 0
	v_mov_b64_e32 v[14:15], 0
	v_mov_b64_e32 v[16:17], 0
	v_mov_b64_e32 v[18:19], 0
	v_mov_b64_e32 v[20:21], 0
	v_mov_b64_e32 v[22:23], 0
	v_mov_b64_e32 v[24:25], 0
	v_mov_b64_e32 v[26:27], 0
	v_mov_b64_e32 v[28:29], 0
	v_mov_b64_e32 v[30:31], 0
	v_mov_b64_e32 v[32:33], 0
	v_mov_b64_e32 v[34:35], 0
	v_mov_b64_e32 v[36:37], 0
	v_mov_b64_e32 v[38:39], 0
	v_mov_b64_e32 v[40:41], 0
	v_mov_b64_e32 v[42:43], 0
	v_mov_b64_e32 v[44:45], 0
	v_mov_b64_e32 v[46:47], 0
	v_mov_b64_e32 v[48:49], 0
	v_mov_b64_e32 v[50:51], 0
	v_mov_b64_e32 v[52:53], 0
	v_mov_b64_e32 v[54:55], 0
	v_mov_b64_e32 v[56:57], 0
	v_mov_b64_e32 v[58:59], 0
	v_mov_b64_e32 v[60:61], 0
	v_mov_b64_e32 v[62:63], 0
	v_mov_b64_e32 v[64:65], 0
	v_mov_b64_e32 v[66:67], 0
	v_mov_b64_e32 v[68:69], 0
	v_mov_b64_e32 v[70:71], 0
	v_mov_b64_e32 v[72:73], 0
	v_mov_b64_e32 v[74:75], 0
	v_mov_b64_e32 v[76:77], 0
	v_mov_b64_e32 v[78:79], 0
	v_mov_b64_e32 v[80:81], 0
	v_mov_b64_e32 v[82:83], 0
	v_mov_b64_e32 v[84:85], 0
	v_mov_b64_e32 v[86:87], 0
	v_mov_b64_e32 v[88:89], 0
	v_mov_b64_e32 v[90:91], 0
	v_mov_b64_e32 v[92:93], 0
	v_mov_b64_e32 v[94:95], 0
	v_mov_b64_e32 v[96:97], 0
	v_mov_b64_e32 v[98:99], 0
	v_mov_b64_e32 v[100:101], 0
	v_mov_b64_e32 v[102:103], 0
	v_mov_b64_e32 v[104:105], 0
	v_mov_b64_e32 v[106:107], 0
	v_mov_b64_e32 v[108:109], 0
	v_mov_b64_e32 v[110:111], 0
	v_mov_b64_e32 v[112:113], 0
	v_mov_b64_e32 v[114:115], 0
	v_mov_b64_e32 v[116:117], 0
	v_mov_b64_e32 v[118:119], 0
	v_mov_b64_e32 v[120:121], 0
	v_mov_b64_e32 v[122:123], 0
	v_mov_b64_e32 v[124:125], 0
	v_mov_b64_e32 v[126:127], 0
	s_addc_u32 s59, s27, 0
	s_mov_b32 s60, -2
	.p2alignl 6, 3212836864

.LBB0_588:
	s_ashr_i32 s35, s34, 31
	s_lshl_b64 s[36:37], s[34:35], 20
	s_add_u32 s36, s60, s36
	s_addc_u32 s37, s61, s37
	s_and_b64 s[38:39], s[8:9], exec
	s_cselect_b32 s35, s37, s49
	s_cselect_b32 s41, s36, s48
	s_ashr_i32 s31, s30, 31
	s_lshl_b64 s[38:39], s[30:31], 20
	s_add_u32 s38, s62, s38
	s_addc_u32 s39, s63, s39
	s_and_b64 s[54:55], s[8:9], exec
	s_cselect_b32 s31, s39, s51
	s_cselect_b32 s73, s38, s50
	s_add_u32 s48, s48, 0x80080
	s_addc_u32 s49, s49, 0
	s_add_u32 s74, s50, 0x100
	v_mov_b32_e32 v0, 0
	v_mov_b64_e32 v[0:1], 0
	v_mov_b64_e32 v[2:3], 0
	v_mov_b64_e32 v[4:5], 0
	v_mov_b64_e32 v[6:7], 0
	v_mov_b64_e32 v[8:9], 0
	v_mov_b64_e32 v[10:11], 0
	v_mov_b64_e32 v[12:13], 0
	v_mov_b64_e32 v[14:15], 0
	v_mov_b64_e32 v[16:17], 0
	v_mov_b64_e32 v[18:19], 0
	v_mov_b64_e32 v[20:21], 0
	v_mov_b64_e32 v[22:23], 0
	v_mov_b64_e32 v[24:25], 0
	v_mov_b64_e32 v[26:27], 0
	v_mov_b64_e32 v[28:29], 0
	v_mov_b64_e32 v[30:31], 0
	v_mov_b64_e32 v[32:33], 0
	v_mov_b64_e32 v[34:35], 0
	v_mov_b64_e32 v[36:37], 0
	v_mov_b64_e32 v[38:39], 0
	v_mov_b64_e32 v[40:41], 0
	v_mov_b64_e32 v[42:43], 0
	v_mov_b64_e32 v[44:45], 0
	v_mov_b64_e32 v[46:47], 0
	v_mov_b64_e32 v[48:49], 0
	v_mov_b64_e32 v[50:51], 0
	v_mov_b64_e32 v[52:53], 0
	v_mov_b64_e32 v[54:55], 0
	v_mov_b64_e32 v[56:57], 0
	v_mov_b64_e32 v[58:59], 0
	v_mov_b64_e32 v[60:61], 0
	v_mov_b64_e32 v[62:63], 0
	v_mov_b64_e32 v[64:65], 0
	v_mov_b64_e32 v[66:67], 0
	v_mov_b64_e32 v[68:69], 0
	v_mov_b64_e32 v[70:71], 0
	v_mov_b64_e32 v[72:73], 0
	v_mov_b64_e32 v[74:75], 0
	v_mov_b64_e32 v[76:77], 0
	v_mov_b64_e32 v[78:79], 0
	v_mov_b64_e32 v[80:81], 0
	v_mov_b64_e32 v[82:83], 0
	v_mov_b64_e32 v[84:85], 0
	v_mov_b64_e32 v[86:87], 0
	v_mov_b64_e32 v[88:89], 0
	v_mov_b64_e32 v[90:91], 0
	v_mov_b64_e32 v[92:93], 0
	v_mov_b64_e32 v[94:95], 0
	v_mov_b64_e32 v[96:97], 0
	v_mov_b64_e32 v[98:99], 0
	v_mov_b64_e32 v[100:101], 0
	v_mov_b64_e32 v[102:103], 0
	v_mov_b64_e32 v[104:105], 0
	v_mov_b64_e32 v[106:107], 0
	v_mov_b64_e32 v[108:109], 0
	v_mov_b64_e32 v[110:111], 0
	v_mov_b64_e32 v[112:113], 0
	v_mov_b64_e32 v[114:115], 0
	v_mov_b64_e32 v[116:117], 0
	v_mov_b64_e32 v[118:119], 0
	v_mov_b64_e32 v[120:121], 0
	v_mov_b64_e32 v[122:123], 0
	v_mov_b64_e32 v[124:125], 0
	v_mov_b64_e32 v[126:127], 0
	s_addc_u32 s75, s51, 0
	s_mov_b32 s77, -2
	s_waitcnt lgkmcnt(0)
	.p2alignl 6, 3212836864

.LBB0_672:
	s_ashr_i32 s25, s24, 31
	s_lshl_b64 s[26:27], s[24:25], 20
	s_add_u32 s26, s38, s26
	s_addc_u32 s27, s39, s27
	s_and_b64 s[28:29], s[6:7], exec
	s_cselect_b32 s25, s27, s31
	s_cselect_b32 s65, s26, s30
	s_ashr_i32 s23, s22, 31
	s_lshl_b64 s[28:29], s[22:23], 20
	s_add_u32 s28, s40, s28
	s_addc_u32 s29, s41, s29
	s_and_b64 s[36:37], s[6:7], exec
	s_cselect_b32 s23, s29, s35
	s_cselect_b32 s66, s28, s34
	s_add_u32 s30, s30, 0x80080
	s_addc_u32 s31, s31, 0
	s_add_u32 s67, s34, 0x100
	v_mov_b32_e32 v8, 0
	v_mov_b64_e32 v[0:1], 0
	v_mov_b64_e32 v[2:3], 0
	v_mov_b64_e32 v[4:5], 0
	v_mov_b64_e32 v[6:7], 0
	v_mov_b64_e32 v[8:9], 0
	v_mov_b64_e32 v[10:11], 0
	v_mov_b64_e32 v[12:13], 0
	v_mov_b64_e32 v[14:15], 0
	v_mov_b64_e32 v[16:17], 0
	v_mov_b64_e32 v[18:19], 0
	v_mov_b64_e32 v[20:21], 0
	v_mov_b64_e32 v[22:23], 0
	v_mov_b64_e32 v[24:25], 0
	v_mov_b64_e32 v[26:27], 0
	v_mov_b64_e32 v[28:29], 0
	v_mov_b64_e32 v[30:31], 0
	v_mov_b64_e32 v[32:33], 0
	v_mov_b64_e32 v[34:35], 0
	v_mov_b64_e32 v[36:37], 0
	v_mov_b64_e32 v[38:39], 0
	v_mov_b64_e32 v[40:41], 0
	v_mov_b64_e32 v[42:43], 0
	v_mov_b64_e32 v[44:45], 0
	v_mov_b64_e32 v[46:47], 0
	v_mov_b64_e32 v[48:49], 0
	v_mov_b64_e32 v[50:51], 0
	v_mov_b64_e32 v[52:53], 0
	v_mov_b64_e32 v[54:55], 0
	v_mov_b64_e32 v[56:57], 0
	v_mov_b64_e32 v[58:59], 0
	v_mov_b64_e32 v[60:61], 0
	v_mov_b64_e32 v[62:63], 0
	v_mov_b64_e32 v[64:65], 0
	v_mov_b64_e32 v[66:67], 0
	v_mov_b64_e32 v[68:69], 0
	v_mov_b64_e32 v[70:71], 0
	v_mov_b64_e32 v[72:73], 0
	v_mov_b64_e32 v[74:75], 0
	v_mov_b64_e32 v[76:77], 0
	v_mov_b64_e32 v[78:79], 0
	v_mov_b64_e32 v[80:81], 0
	v_mov_b64_e32 v[82:83], 0
	v_mov_b64_e32 v[84:85], 0
	v_mov_b64_e32 v[86:87], 0
	v_mov_b64_e32 v[88:89], 0
	v_mov_b64_e32 v[90:91], 0
	v_mov_b64_e32 v[92:93], 0
	v_mov_b64_e32 v[94:95], 0
	v_mov_b64_e32 v[96:97], 0
	v_mov_b64_e32 v[98:99], 0
	v_mov_b64_e32 v[100:101], 0
	v_mov_b64_e32 v[102:103], 0
	v_mov_b64_e32 v[104:105], 0
	v_mov_b64_e32 v[106:107], 0
	v_mov_b64_e32 v[108:109], 0
	v_mov_b64_e32 v[110:111], 0
	v_mov_b64_e32 v[112:113], 0
	v_mov_b64_e32 v[114:115], 0
	v_mov_b64_e32 v[116:117], 0
	v_mov_b64_e32 v[118:119], 0
	v_mov_b64_e32 v[120:121], 0
	v_mov_b64_e32 v[122:123], 0
	v_mov_b64_e32 v[124:125], 0
	v_mov_b64_e32 v[126:127], 0
	s_addc_u32 s68, s35, 0
	s_mov_b32 s69, -2
	.p2alignl 6, 3212836864

.LBB0_1186:
	s_add_u32 s66, s30, 0x100
	v_mov_b32_e32 v0, 0
	v_mov_b64_e32 v[0:1], 0
	v_mov_b64_e32 v[2:3], 0
	v_mov_b64_e32 v[4:5], 0
	v_mov_b64_e32 v[6:7], 0
	v_mov_b64_e32 v[8:9], 0
	v_mov_b64_e32 v[10:11], 0
	v_mov_b64_e32 v[12:13], 0
	v_mov_b64_e32 v[14:15], 0
	v_mov_b64_e32 v[16:17], 0
	v_mov_b64_e32 v[18:19], 0
	v_mov_b64_e32 v[20:21], 0
	v_mov_b64_e32 v[22:23], 0
	v_mov_b64_e32 v[24:25], 0
	v_mov_b64_e32 v[26:27], 0
	v_mov_b64_e32 v[28:29], 0
	v_mov_b64_e32 v[30:31], 0
	v_mov_b64_e32 v[32:33], 0
	v_mov_b64_e32 v[34:35], 0
	v_mov_b64_e32 v[36:37], 0
	v_mov_b64_e32 v[38:39], 0
	v_mov_b64_e32 v[40:41], 0
	v_mov_b64_e32 v[42:43], 0
	v_mov_b64_e32 v[44:45], 0
	v_mov_b64_e32 v[46:47], 0
	v_mov_b64_e32 v[48:49], 0
	v_mov_b64_e32 v[50:51], 0
	v_mov_b64_e32 v[52:53], 0
	v_mov_b64_e32 v[54:55], 0
	v_mov_b64_e32 v[56:57], 0
	v_mov_b64_e32 v[58:59], 0
	v_mov_b64_e32 v[60:61], 0
	v_mov_b64_e32 v[62:63], 0
	v_mov_b64_e32 v[64:65], 0
	v_mov_b64_e32 v[66:67], 0
	v_mov_b64_e32 v[68:69], 0
	v_mov_b64_e32 v[70:71], 0
	v_mov_b64_e32 v[72:73], 0
	v_mov_b64_e32 v[74:75], 0
	v_mov_b64_e32 v[76:77], 0
	v_mov_b64_e32 v[78:79], 0
	v_mov_b64_e32 v[80:81], 0
	v_mov_b64_e32 v[82:83], 0
	v_mov_b64_e32 v[84:85], 0
	v_mov_b64_e32 v[86:87], 0
	v_mov_b64_e32 v[88:89], 0
	v_mov_b64_e32 v[90:91], 0
	v_mov_b64_e32 v[92:93], 0
	v_mov_b64_e32 v[94:95], 0
	v_mov_b64_e32 v[96:97], 0
	v_mov_b64_e32 v[98:99], 0
	v_mov_b64_e32 v[100:101], 0
	v_mov_b64_e32 v[102:103], 0
	v_mov_b64_e32 v[104:105], 0
	v_mov_b64_e32 v[106:107], 0
	v_mov_b64_e32 v[108:109], 0
	v_mov_b64_e32 v[110:111], 0
	v_mov_b64_e32 v[112:113], 0
	v_mov_b64_e32 v[114:115], 0
	v_mov_b64_e32 v[116:117], 0
	v_mov_b64_e32 v[118:119], 0
	v_mov_b64_e32 v[120:121], 0
	v_mov_b64_e32 v[122:123], 0
	v_mov_b64_e32 v[124:125], 0
	v_mov_b64_e32 v[126:127], 0
	s_addc_u32 s67, s31, 0
	s_mov_b32 s68, -2
	s_waitcnt lgkmcnt(0)
	.p2alignl 6, 3212836864

.LBB0_1270:
	s_ashr_i32 s25, s24, 31
	s_lshl_b64 s[26:27], s[24:25], 20
	s_add_u32 s26, s38, s26
	s_addc_u32 s27, s39, s27
	s_and_b64 s[28:29], s[6:7], exec
	s_cselect_b32 s25, s27, s31
	s_cselect_b32 s63, s26, s30
	s_ashr_i32 s23, s22, 31
	s_lshl_b64 s[28:29], s[22:23], 20
	s_add_u32 s28, s40, s28
	s_addc_u32 s29, s41, s29
	s_and_b64 s[36:37], s[6:7], exec
	s_cselect_b32 s23, s29, s35
	s_cselect_b32 s64, s28, s34
	s_add_u32 s30, s30, 0x80080
	s_addc_u32 s31, s31, 0
	s_add_u32 s65, s34, 0x100
	v_mov_b32_e32 v0, 0
	v_mov_b64_e32 v[0:1], 0
	v_mov_b64_e32 v[2:3], 0
	v_mov_b64_e32 v[4:5], 0
	v_mov_b64_e32 v[6:7], 0
	v_mov_b64_e32 v[8:9], 0
	v_mov_b64_e32 v[10:11], 0
	v_mov_b64_e32 v[12:13], 0
	v_mov_b64_e32 v[14:15], 0
	v_mov_b64_e32 v[16:17], 0
	v_mov_b64_e32 v[18:19], 0
	v_mov_b64_e32 v[20:21], 0
	v_mov_b64_e32 v[22:23], 0
	v_mov_b64_e32 v[24:25], 0
	v_mov_b64_e32 v[26:27], 0
	v_mov_b64_e32 v[28:29], 0
	v_mov_b64_e32 v[30:31], 0
	v_mov_b64_e32 v[32:33], 0
	v_mov_b64_e32 v[34:35], 0
	v_mov_b64_e32 v[36:37], 0
	v_mov_b64_e32 v[38:39], 0
	v_mov_b64_e32 v[40:41], 0
	v_mov_b64_e32 v[42:43], 0
	v_mov_b64_e32 v[44:45], 0
	v_mov_b64_e32 v[46:47], 0
	v_mov_b64_e32 v[48:49], 0
	v_mov_b64_e32 v[50:51], 0
	v_mov_b64_e32 v[52:53], 0
	v_mov_b64_e32 v[54:55], 0
	v_mov_b64_e32 v[56:57], 0
	v_mov_b64_e32 v[58:59], 0
	v_mov_b64_e32 v[60:61], 0
	v_mov_b64_e32 v[62:63], 0
	v_mov_b64_e32 v[64:65], 0
	v_mov_b64_e32 v[66:67], 0
	v_mov_b64_e32 v[68:69], 0
	v_mov_b64_e32 v[70:71], 0
	v_mov_b64_e32 v[72:73], 0
	v_mov_b64_e32 v[74:75], 0
	v_mov_b64_e32 v[76:77], 0
	v_mov_b64_e32 v[78:79], 0
	v_mov_b64_e32 v[80:81], 0
	v_mov_b64_e32 v[82:83], 0
	v_mov_b64_e32 v[84:85], 0
	v_mov_b64_e32 v[86:87], 0
	v_mov_b64_e32 v[88:89], 0
	v_mov_b64_e32 v[90:91], 0
	v_mov_b64_e32 v[92:93], 0
	v_mov_b64_e32 v[94:95], 0
	v_mov_b64_e32 v[96:97], 0
	v_mov_b64_e32 v[98:99], 0
	v_mov_b64_e32 v[100:101], 0
	v_mov_b64_e32 v[102:103], 0
	v_mov_b64_e32 v[104:105], 0
	v_mov_b64_e32 v[106:107], 0
	v_mov_b64_e32 v[108:109], 0
	v_mov_b64_e32 v[110:111], 0
	v_mov_b64_e32 v[112:113], 0
	v_mov_b64_e32 v[114:115], 0
	v_mov_b64_e32 v[116:117], 0
	v_mov_b64_e32 v[118:119], 0
	v_mov_b64_e32 v[120:121], 0
	v_mov_b64_e32 v[122:123], 0
	v_mov_b64_e32 v[124:125], 0
	v_mov_b64_e32 v[126:127], 0
	s_addc_u32 s66, s35, 0
	s_mov_b32 s67, -2
	.p2alignl 6, 3212836864

.LBB0_1419:
	s_ashr_i32 s27, s26, 31
	s_lshl_b64 s[28:29], s[26:27], 20
	s_add_u32 s28, s48, s28
	s_addc_u32 s29, s49, s29
	s_and_b64 s[30:31], s[8:9], exec
	s_cselect_b32 s27, s29, s39
	s_cselect_b32 s35, s28, s38
	s_ashr_i32 s25, s24, 31
	s_lshl_b64 s[30:31], s[24:25], 20
	s_add_u32 s30, s50, s30
	s_addc_u32 s31, s51, s31
	s_and_b64 s[42:43], s[8:9], exec
	s_cselect_b32 s25, s31, s41
	s_cselect_b32 s65, s30, s40
	s_add_u32 s38, s38, 0x80080
	s_addc_u32 s39, s39, 0
	s_add_u32 s66, s40, 0x100
	v_mov_b32_e32 v0, 0
	v_mov_b64_e32 v[0:1], 0
	v_mov_b64_e32 v[2:3], 0
	v_mov_b64_e32 v[4:5], 0
	v_mov_b64_e32 v[6:7], 0
	v_mov_b64_e32 v[8:9], 0
	v_mov_b64_e32 v[10:11], 0
	v_mov_b64_e32 v[12:13], 0
	v_mov_b64_e32 v[14:15], 0
	v_mov_b64_e32 v[16:17], 0
	v_mov_b64_e32 v[18:19], 0
	v_mov_b64_e32 v[20:21], 0
	v_mov_b64_e32 v[22:23], 0
	v_mov_b64_e32 v[24:25], 0
	v_mov_b64_e32 v[26:27], 0
	v_mov_b64_e32 v[28:29], 0
	v_mov_b64_e32 v[30:31], 0
	v_mov_b64_e32 v[32:33], 0
	v_mov_b64_e32 v[34:35], 0
	v_mov_b64_e32 v[36:37], 0
	v_mov_b64_e32 v[38:39], 0
	v_mov_b64_e32 v[40:41], 0
	v_mov_b64_e32 v[42:43], 0
	v_mov_b64_e32 v[44:45], 0
	v_mov_b64_e32 v[46:47], 0
	v_mov_b64_e32 v[48:49], 0
	v_mov_b64_e32 v[50:51], 0
	v_mov_b64_e32 v[52:53], 0
	v_mov_b64_e32 v[54:55], 0
	v_mov_b64_e32 v[56:57], 0
	v_mov_b64_e32 v[58:59], 0
	v_mov_b64_e32 v[60:61], 0
	v_mov_b64_e32 v[62:63], 0
	v_mov_b64_e32 v[64:65], 0
	v_mov_b64_e32 v[66:67], 0
	v_mov_b64_e32 v[68:69], 0
	v_mov_b64_e32 v[70:71], 0
	v_mov_b64_e32 v[72:73], 0
	v_mov_b64_e32 v[74:75], 0
	v_mov_b64_e32 v[76:77], 0
	v_mov_b64_e32 v[78:79], 0
	v_mov_b64_e32 v[80:81], 0
	v_mov_b64_e32 v[82:83], 0
	v_mov_b64_e32 v[84:85], 0
	v_mov_b64_e32 v[86:87], 0
	v_mov_b64_e32 v[88:89], 0
	v_mov_b64_e32 v[90:91], 0
	v_mov_b64_e32 v[92:93], 0
	v_mov_b64_e32 v[94:95], 0
	v_mov_b64_e32 v[96:97], 0
	v_mov_b64_e32 v[98:99], 0
	v_mov_b64_e32 v[100:101], 0
	v_mov_b64_e32 v[102:103], 0
	v_mov_b64_e32 v[104:105], 0
	v_mov_b64_e32 v[106:107], 0
	v_mov_b64_e32 v[108:109], 0
	v_mov_b64_e32 v[110:111], 0
	v_mov_b64_e32 v[112:113], 0
	v_mov_b64_e32 v[114:115], 0
	v_mov_b64_e32 v[116:117], 0
	v_mov_b64_e32 v[118:119], 0
	v_mov_b64_e32 v[120:121], 0
	v_mov_b64_e32 v[122:123], 0
	v_mov_b64_e32 v[124:125], 0
	v_mov_b64_e32 v[126:127], 0
	s_addc_u32 s67, s41, 0
	s_mov_b32 s68, -2
	s_waitcnt lgkmcnt(0)
	.p2alignl 6, 3212836864

.LBB0_1503:
	s_ashr_i32 s23, s22, 31
	s_lshl_b64 s[24:25], s[22:23], 20
	s_add_u32 s24, s36, s24
	s_addc_u32 s25, s37, s25
	s_and_b64 s[26:27], s[6:7], exec
	s_cselect_b32 s23, s25, s29
	s_cselect_b32 s61, s24, s28
	s_ashr_i32 s21, s20, 31
	s_lshl_b64 s[26:27], s[20:21], 20
	s_add_u32 s26, s38, s26
	s_addc_u32 s27, s39, s27
	s_and_b64 s[34:35], s[6:7], exec
	s_cselect_b32 s21, s27, s31
	s_cselect_b32 s62, s26, s30
	s_add_u32 s28, s28, 0x80080
	s_addc_u32 s29, s29, 0
	s_add_u32 s63, s30, 0x100
	v_mov_b32_e32 v8, 0
	v_mov_b64_e32 v[0:1], 0
	v_mov_b64_e32 v[2:3], 0
	v_mov_b64_e32 v[4:5], 0
	v_mov_b64_e32 v[6:7], 0
	v_mov_b64_e32 v[8:9], 0
	v_mov_b64_e32 v[10:11], 0
	v_mov_b64_e32 v[12:13], 0
	v_mov_b64_e32 v[14:15], 0
	v_mov_b64_e32 v[16:17], 0
	v_mov_b64_e32 v[18:19], 0
	v_mov_b64_e32 v[20:21], 0
	v_mov_b64_e32 v[22:23], 0
	v_mov_b64_e32 v[24:25], 0
	v_mov_b64_e32 v[26:27], 0
	v_mov_b64_e32 v[28:29], 0
	v_mov_b64_e32 v[30:31], 0
	v_mov_b64_e32 v[32:33], 0
	v_mov_b64_e32 v[34:35], 0
	v_mov_b64_e32 v[36:37], 0
	v_mov_b64_e32 v[38:39], 0
	v_mov_b64_e32 v[40:41], 0
	v_mov_b64_e32 v[42:43], 0
	v_mov_b64_e32 v[44:45], 0
	v_mov_b64_e32 v[46:47], 0
	v_mov_b64_e32 v[48:49], 0
	v_mov_b64_e32 v[50:51], 0
	v_mov_b64_e32 v[52:53], 0
	v_mov_b64_e32 v[54:55], 0
	v_mov_b64_e32 v[56:57], 0
	v_mov_b64_e32 v[58:59], 0
	v_mov_b64_e32 v[60:61], 0
	v_mov_b64_e32 v[62:63], 0
	v_mov_b64_e32 v[64:65], 0
	v_mov_b64_e32 v[66:67], 0
	v_mov_b64_e32 v[68:69], 0
	v_mov_b64_e32 v[70:71], 0
	v_mov_b64_e32 v[72:73], 0
	v_mov_b64_e32 v[74:75], 0
	v_mov_b64_e32 v[76:77], 0
	v_mov_b64_e32 v[78:79], 0
	v_mov_b64_e32 v[80:81], 0
	v_mov_b64_e32 v[82:83], 0
	v_mov_b64_e32 v[84:85], 0
	v_mov_b64_e32 v[86:87], 0
	v_mov_b64_e32 v[88:89], 0
	v_mov_b64_e32 v[90:91], 0
	v_mov_b64_e32 v[92:93], 0
	v_mov_b64_e32 v[94:95], 0
	v_mov_b64_e32 v[96:97], 0
	v_mov_b64_e32 v[98:99], 0
	v_mov_b64_e32 v[100:101], 0
	v_mov_b64_e32 v[102:103], 0
	v_mov_b64_e32 v[104:105], 0
	v_mov_b64_e32 v[106:107], 0
	v_mov_b64_e32 v[108:109], 0
	v_mov_b64_e32 v[110:111], 0
	v_mov_b64_e32 v[112:113], 0
	v_mov_b64_e32 v[114:115], 0
	v_mov_b64_e32 v[116:117], 0
	v_mov_b64_e32 v[118:119], 0
	v_mov_b64_e32 v[120:121], 0
	v_mov_b64_e32 v[122:123], 0
	v_mov_b64_e32 v[124:125], 0
	v_mov_b64_e32 v[126:127], 0
	s_addc_u32 s64, s31, 0
	s_mov_b32 s65, -2
	.p2alignl 6, 3212836864
